# v10 with P1 tile order: per-round per-XCD block permutation (blocks of 4 WGs) replacing the per-round rotation, balances expensive column tiles
# speedup vs baseline: 1.0079x; 1.0079x over previous
.LBB0_143:
	s_add_i32 s71, s71, 1
	s_and_b32 s99, s2, 7
	s_cmp_eq_u32 s71, 1
	s_cbranch_scc1 .Lp1r1
	s_cmp_eq_u32 s71, 2
	s_cbranch_scc1 .Lp1r2
	s_cmp_eq_u32 s71, 3
	s_cbranch_scc1 .Lp1r3
	s_cmp_eq_u32 s71, 4
	s_cbranch_scc1 .Lp1r4
	s_cmp_eq_u32 s71, 5
	s_cbranch_scc1 .Lp1r5
	s_cmp_eq_u32 s71, 6
	s_cbranch_scc1 .Lp1r6
	s_mov_b32 s98, 0xfac688
	s_branch .Lp1rdone
.Lp1r1:
	s_mov_b32 s98, 0xaf8991
	s_cmp_eq_u32 s99, 1
	s_cmov_b32 s98, 0x7903ec
	s_cmp_eq_u32 s99, 2
	s_cmov_b32 s98, 0x77113a
	s_cmp_eq_u32 s99, 3
	s_cmov_b32 s98, 0x383b3a
	s_cmp_eq_u32 s99, 4
	s_cmov_b32 s98, 0x17e70a
	s_cmp_eq_u32 s99, 5
	s_cmov_b32 s98, 0x1327cd
	s_cmp_eq_u32 s99, 6
	s_cmov_b32 s98, 0xf2e611
	s_cmp_eq_u32 s99, 7
	s_cmov_b32 s98, 0xd2be42
	s_branch .Lp1rdone
.Lp1r2:
	s_mov_b32 s98, 0x973478
	s_cmp_eq_u32 s99, 1
	s_cmov_b32 s98, 0xcb9163
	s_cmp_eq_u32 s99, 2
	s_cmov_b32 s98, 0x7bca0a
	s_cmp_eq_u32 s99, 3
	s_cmov_b32 s98, 0xf8195a
	s_cmp_eq_u32 s99, 4
	s_cmov_b32 s98, 0xd2be81
	s_cmp_eq_u32 s99, 5
	s_cmov_b32 s98, 0xcec287
	s_cmp_eq_u32 s99, 6
	s_cmov_b32 s98, 0x358dd4
	s_cmp_eq_u32 s99, 7
	s_cmov_b32 s98, 0x86a63e
	s_branch .Lp1rdone
.Lp1r3:
	s_mov_b32 s98, 0x5a98f8
	s_cmp_eq_u32 s99, 1
	s_cmov_b32 s98, 0xc2ceca
	s_cmp_eq_u32 s99, 2
	s_cmov_b32 s98, 0xef5842
	s_cmp_eq_u32 s99, 3
	s_cmov_b32 s98, 0xabbc44
	s_cmp_eq_u32 s99, 4
	s_cmov_b32 s98, 0x9f10ab
	s_cmp_eq_u32 s99, 5
	s_cmov_b32 s98, 0x6af384
	s_cmp_eq_u32 s99, 6
	s_cmov_b32 s98, 0x83545f
	s_cmp_eq_u32 s99, 7
	s_cmov_b32 s98, 0x645eb4
	s_branch .Lp1rdone
.Lp1r4:
	s_mov_b32 s98, 0x757e2
	s_cmp_eq_u32 s99, 1
	s_cmov_b32 s98, 0xde5213
	s_cmp_eq_u32 s99, 2
	s_cmov_b32 s98, 0x9cd6b0
	s_cmp_eq_u32 s99, 3
	s_cmov_b32 s98, 0x7cdd02
	s_cmp_eq_u32 s99, 4
	s_cmov_b32 s98, 0x5467cc
	s_cmp_eq_u32 s99, 5
	s_cmov_b32 s98, 0x4f832e
	s_cmp_eq_u32 s99, 6
	s_cmov_b32 s98, 0x342d1f
	s_cmp_eq_u32 s99, 7
	s_cmov_b32 s98, 0x57d1d
	s_branch .Lp1rdone
.Lp1r5:
	s_mov_b32 s98, 0xbbc08b
	s_cmp_eq_u32 s99, 1
	s_cmov_b32 s98, 0xe44ad6
	s_cmp_eq_u32 s99, 2
	s_cmov_b32 s98, 0x8ce5e8
	s_cmp_eq_u32 s99, 3
	s_cmov_b32 s98, 0x7c294e
	s_cmp_eq_u32 s99, 4
	s_cmov_b32 s98, 0x5cd0f4
	s_cmp_eq_u32 s99, 5
	s_cmov_b32 s98, 0x9702fa
	s_cmp_eq_u32 s99, 6
	s_cmov_b32 s98, 0x8c7395
	s_cmp_eq_u32 s99, 7
	s_cmov_b32 s98, 0xd10acf
	s_branch .Lp1rdone
.Lp1r6:
	s_mov_b32 s98, 0xe9d80e
	s_cmp_eq_u32 s99, 1
	s_cmov_b32 s98, 0xde86a1
	s_cmp_eq_u32 s99, 2
	s_cmov_b32 s98, 0xde98d0
	s_cmp_eq_u32 s99, 3
	s_cmov_b32 s98, 0xbba660
	s_cmp_eq_u32 s99, 4
	s_cmov_b32 s98, 0xfac688
	s_cmp_eq_u32 s99, 5
	s_cmov_b32 s98, 0xf2e05a
	s_cmp_eq_u32 s99, 6
	s_cmov_b32 s98, 0xcab847
	s_cmp_eq_u32 s99, 7
	s_cmov_b32 s98, 0xa0fd1a
.Lp1rdone:
	s_lshr_b32 s100, s2, 3
	s_lshr_b32 s101, s100, 2
	s_mul_i32 s101, s101, 3
	s_lshr_b32 s98, s98, s101
	s_and_b32 s98, s98, 7
	s_lshl_b32 s98, s98, 2
	s_and_b32 s100, s100, 3
	s_or_b32 s98, s98, s100
	s_lshl_b32 s98, s98, 3
	s_or_b32 s98, s98, s99
	s_mul_i32 s10, s71, s97
	s_mul_hi_u32 s11, s71, s96
	s_add_i32 s11, s11, s10
	s_mul_i32 s10, s71, s96
	s_add_u32 s10, s10, s98
	s_addc_u32 s11, s11, s3
	v_cmp_gt_i64_e32 vcc, s[10:11], v[162:163]
	v_cmp_lt_i64_e64 s[38:39], s[10:11], v[160:161]
	s_cbranch_vccnz .LBB0_149
	s_ashr_i32 s11, s10, 31
	s_lshr_b32 s11, s11, 29
	s_add_i32 s20, s10, s11
	s_and_b32 s11, s20, -8
	s_sub_i32 s21, s10, s11
	s_cmp_gt_i32 s21, 1
	s_mov_b64 s[10:11], -1
	s_cbranch_scc0 .LBB0_146
	s_mul_i32 s10, s21, 0xd3
	s_add_i32 s22, s10, 2
	s_mov_b64 s[10:11], 0
